# attention: row-max and sum-of-squares cross-row reductions via v_permlane16_swap/v_permlane32_swap instead of ds_bpermute LDS round trips (bit-identical)
# baseline (speedup 1.0000x reference)
.LBB0_446:
	s_add_i32 s16, s16, s2
	s_max_i32 s11, s16, 4
	s_ashr_i32 s10, s15, 8
	s_add_i32 s11, s11, -4
	s_min_u32 s1, s17, 49
	s_min_u32 s12, s11, 56
	s_ashr_i32 s11, s10, 31
	s_and_b32 s0, s14, 48
	s_sub_i32 s13, s12, s1
	s_lshl_b64 s[10:11], s[10:11], 12
	s_lshl_b32 s1, s16, 6
	s_add_u32 s10, s10, s1
	s_addc_u32 s1, s11, 0
	s_lshl_b32 s46, s13, 12
	v_add_u32_e32 v83, s46, v182
	v_add_u32_e32 v129, v83, v177
	v_add_u32_e32 v131, v83, v178
	ds_read_b128 v[84:87], v129
	ds_read_b128 v[88:91], v129 offset:512
	ds_read_b128 v[92:95], v131
	ds_read_b128 v[96:99], v131 offset:512
	s_waitcnt vmcnt(18) lgkmcnt(3)
	v_mfma_f32_16x16x32_bf16 v[84:87], v[84:87], v[78:81], 0
	v_sub_u32_e64 v82, s0, 8 clamp
	v_min_u32_e32 v133, 32, v82
	v_or_b32_e32 v135, s0, v173
	s_waitcnt lgkmcnt(2)
	v_mfma_f32_16x16x32_bf16 v[88:91], v[88:91], v[78:81], 0
	s_or_b32 s0, s10, s0
	s_lshl_b64 s[0:1], s[0:1], 11
	s_add_i32 s47, s46, 0x1000
	s_waitcnt lgkmcnt(1)
	v_mfma_f32_16x16x32_bf16 v[188:191], v[92:95], v[74:77], v[84:87]
	s_add_i32 s45, s46, 0x2000
	s_add_i32 s44, s46, 0x3000
	s_add_i32 s43, s46, 0x4000
	s_waitcnt lgkmcnt(0)
	v_mfma_f32_16x16x32_bf16 v[192:195], v[96:99], v[74:77], v[88:91]
	ds_read_b128 v[84:87], v129 offset:4096
	s_nop 1
	ds_read_b128 v[88:91], v129 offset:4608
	ds_read_b128 v[92:95], v131 offset:4096
	ds_read_b128 v[96:99], v131 offset:4608
	s_add_i32 s42, s46, 0x5000
	s_waitcnt lgkmcnt(3)
	v_mfma_f32_16x16x32_bf16 v[84:87], v[84:87], v[78:81], 0
	s_add_i32 s41, s46, 0x6000
	s_add_i32 s40, s46, 0x7000
	s_add_u32 s38, s80, s0
	s_waitcnt lgkmcnt(1)
	v_mfma_f32_16x16x32_bf16 v[196:199], v[92:95], v[74:77], v[84:87]
	s_addc_u32 s39, s81, s1
	s_sub_i32 s0, s12, s16
	s_mulk_i32 s0, 0x7c
	v_mfma_f32_16x16x32_bf16 v[84:87], v[88:91], v[78:81], 0
	s_add_i32 s0, s0, 0
	s_add_i32 s0, s0, 0x1e100
	s_waitcnt lgkmcnt(0)
	v_mfma_f32_16x16x32_bf16 v[200:203], v[96:99], v[74:77], v[84:87]
	s_nop 3
	ds_read_b128 v[84:87], v129 offset:8192
	ds_read_b128 v[88:91], v129 offset:8704
	ds_read_b128 v[92:95], v131 offset:8192
	ds_read_b128 v[96:99], v131 offset:8704
	s_waitcnt lgkmcnt(3)
	v_mfma_f32_16x16x32_bf16 v[84:87], v[84:87], v[78:81], 0
	s_waitcnt lgkmcnt(1)
	v_mfma_f32_16x16x32_bf16 v[122:125], v[92:95], v[74:77], v[84:87]
	ds_read_b128 v[92:95], v131 offset:12288
	v_mfma_f32_16x16x32_bf16 v[84:87], v[88:91], v[78:81], 0
	ds_read_b128 v[88:91], v129 offset:12288
	s_waitcnt lgkmcnt(2)
	v_mfma_f32_16x16x32_bf16 v[118:121], v[96:99], v[74:77], v[84:87]
	v_max_i32_e32 v96, 8, v135
	v_add_u32_e32 v137, -8, v96
	ds_read_b128 v[96:99], v131 offset:12800
	s_nop 1
	ds_read_b128 v[82:85], v129 offset:12800
	s_waitcnt lgkmcnt(2)
	v_mfma_f32_16x16x32_bf16 v[86:89], v[88:91], v[78:81], 0
	v_mfma_f32_16x16x32_bf16 v[110:113], v[92:95], v[74:77], v[86:89]
	ds_read_b128 v[90:93], v131 offset:16384
	s_nop 5
	ds_read_b128 v[86:89], v129 offset:16384
	s_waitcnt lgkmcnt(2)
	v_mfma_f32_16x16x32_bf16 v[82:85], v[82:85], v[78:81], 0
	v_mfma_f32_16x16x32_bf16 v[114:117], v[96:99], v[74:77], v[82:85]
	s_nop 6
	ds_read_b128 v[82:85], v129 offset:16896
	ds_read_b128 v[94:97], v131 offset:16896
	ds_read_b128 v[98:101], v129 offset:20480
	ds_read_b128 v[204:207], v129 offset:20992
	s_waitcnt lgkmcnt(4)
	v_mfma_f32_16x16x32_bf16 v[86:89], v[86:89], v[78:81], 0
	s_waitcnt lgkmcnt(3)
	v_mfma_f32_16x16x32_bf16 v[82:85], v[82:85], v[78:81], 0
	v_mfma_f32_16x16x32_bf16 v[102:105], v[90:93], v[74:77], v[86:89]
	s_nop 4
	ds_read_b128 v[86:89], v131 offset:20480
	ds_read_b128 v[90:93], v131 offset:20992
	ds_read_b128 v[208:211], v129 offset:24576
	ds_read_b128 v[212:215], v129 offset:25088
	ds_read_b128 v[216:219], v131 offset:24576
	ds_read_b128 v[220:223], v131 offset:25088
	ds_read_b128 v[224:227], v129 offset:28672
	ds_read_b128 v[228:231], v129 offset:29184
	s_waitcnt lgkmcnt(10)
	v_mfma_f32_16x16x32_bf16 v[106:109], v[94:97], v[74:77], v[82:85]
	ds_read_b128 v[232:235], v131 offset:28672
	ds_read_b128 v[236:239], v131 offset:29184
	v_add_u32_e32 v131, v133, v142
	v_min_u32_e32 v129, 48, v137
	s_waitcnt lgkmcnt(11)
	v_mfma_f32_16x16x32_bf16 v[82:85], v[98:101], v[78:81], 0
	v_cmp_ge_u32_e32 vcc, v131, v129
	v_or_b32_e32 v139, 1, v131
	v_or_b32_e32 v155, 2, v131
	s_waitcnt lgkmcnt(9)
	v_mfma_f32_16x16x32_bf16 v[94:97], v[86:89], v[74:77], v[82:85]
	v_or_b32_e32 v157, 3, v131
	v_mfma_f32_16x16x32_bf16 v[82:85], v[204:207], v[78:81], 0
	s_waitcnt lgkmcnt(8)
	v_mfma_f32_16x16x32_bf16 v[90:93], v[90:93], v[74:77], v[82:85]
	s_waitcnt lgkmcnt(6)
	v_mfma_f32_16x16x32_bf16 v[86:89], v[212:215], v[78:81], 0
	s_nop 3
	v_sub_u32_e32 v82, v131, v135
	v_lshl_add_u32 v133, v82, 2, s0
	ds_read2_b32 v[204:205], v133 offset0:232 offset1:233
	v_add_u32_e32 v135, 16, v129
	v_cmp_lt_u32_e64 s[0:1], v131, v135
	s_and_b64 vcc, vcc, s[0:1]
	v_mfma_f32_16x16x32_bf16 v[82:85], v[208:211], v[78:81], 0
	s_waitcnt lgkmcnt(0)
	v_add_f32_e32 v98, v188, v204
	v_cndmask_b32_e32 v137, v186, v98, vcc
	ds_read2_b32 v[206:207], v133 offset0:234 offset1:235
	ds_read2_b32 v[208:209], v133 offset0:236 offset1:237
	ds_read2_b32 v[210:211], v133 offset0:238 offset1:239
	v_mfma_f32_16x16x32_bf16 v[98:101], v[220:223], v[74:77], v[86:89]
	v_cmp_ge_u32_e64 s[0:1], v139, v129
	v_cmp_lt_u32_e64 s[10:11], v139, v135
	s_and_b64 s[10:11], s[0:1], s[10:11]
	v_mfma_f32_16x16x32_bf16 v[86:89], v[224:227], v[78:81], 0
	v_cmp_ge_u32_e64 s[0:1], v155, v129
	v_cmp_lt_u32_e64 s[12:13], v155, v135
	v_add_f32_e32 v139, v189, v205
	v_mfma_f32_16x16x32_bf16 v[78:81], v[228:231], v[78:81], 0
	s_and_b64 s[12:13], s[0:1], s[12:13]
	v_cmp_ge_u32_e64 s[0:1], v157, v129
	v_cmp_lt_u32_e64 s[14:15], v157, v135
	v_mfma_f32_16x16x32_bf16 v[82:85], v[216:219], v[74:77], v[82:85]
	v_cndmask_b32_e64 v139, v186, v139, s[10:11]
	s_waitcnt lgkmcnt(2)
	v_add_f32_e32 v155, v190, v206
	s_and_b64 s[14:15], s[0:1], s[14:15]
	v_mfma_f32_16x16x32_bf16 v[86:89], v[232:235], v[74:77], v[86:89]
	v_max3_f32 v141, v137, s33, v139
	v_cndmask_b32_e64 v155, v186, v155, s[12:13]
	v_add_u32_e32 v190, 0x434, v133
	v_mfma_f32_16x16x32_bf16 v[74:77], v[236:239], v[74:77], v[78:81]
	s_nop 2
	v_or_b32_e32 v79, 4, v131
	v_add_f32_e32 v78, v191, v207
	v_cmp_ge_u32_e64 s[0:1], v79, v129
	v_cmp_lt_u32_e64 s[16:17], v79, v135
	v_cndmask_b32_e64 v157, v186, v78, s[14:15]
	s_waitcnt lgkmcnt(1)
	v_add_f32_e32 v79, v192, v208
	s_and_b64 s[16:17], s[0:1], s[16:17]
	v_max3_f32 v78, v141, v155, v157
	v_cndmask_b32_e64 v141, v186, v79, s[16:17]
	v_or_b32_e32 v79, 5, v131
	v_cmp_ge_u32_e64 s[0:1], v79, v129
	v_cmp_lt_u32_e64 s[18:19], v79, v135
	v_add_f32_e32 v79, v193, v209
	s_and_b64 s[18:19], s[0:1], s[18:19]
	v_cndmask_b32_e64 v187, v186, v79, s[18:19]
	v_or_b32_e32 v79, 6, v131
	v_cmp_ge_u32_e64 s[0:1], v79, v129
	v_cmp_lt_u32_e64 s[20:21], v79, v135
	s_waitcnt lgkmcnt(0)
	v_add_f32_e32 v79, v194, v210
	s_and_b64 s[20:21], s[0:1], s[20:21]
	v_cndmask_b32_e64 v192, v186, v79, s[20:21]
	v_or_b32_e32 v79, 7, v131
	v_cmp_ge_u32_e64 s[0:1], v79, v129
	v_cmp_lt_u32_e64 s[22:23], v79, v135
	v_add_f32_e32 v79, v195, v211
	s_and_b64 s[22:23], s[0:1], s[22:23]
	v_max3_f32 v78, v78, v141, v187
	v_cndmask_b32_e64 v129, v186, v79, s[22:23]
	v_max3_f32 v131, v78, v192, v129
	v_add_u32_e32 v78, 0x41c, v133
	ds_read2_b32 v[78:79], v78 offset1:1
	v_add_u32_e32 v80, 0x424, v133
	v_add_u32_e32 v135, 0x42c, v133
	ds_read2_b32 v[80:81], v80 offset1:1
	ds_read2_b32 v[188:189], v135 offset1:1
	ds_read2_b32 v[190:191], v190 offset1:1
	s_lshl_b32 s0, s37, 7
	s_waitcnt lgkmcnt(3)
	v_add_f32_e32 v78, v196, v78
	v_cndmask_b32_e32 v135, v186, v78, vcc
	v_add_f32_e32 v78, v197, v79
	v_cndmask_b32_e64 v193, v186, v78, s[10:11]
	s_waitcnt lgkmcnt(2)
	v_add_f32_e32 v79, v198, v80
	v_max3_f32 v78, v131, v135, v193
	v_cndmask_b32_e64 v131, v186, v79, s[12:13]
	v_add_f32_e32 v79, v199, v81
	v_cndmask_b32_e64 v194, v186, v79, s[14:15]
	s_waitcnt lgkmcnt(1)
	v_add_f32_e32 v79, v200, v188
	v_cndmask_b32_e64 v195, v186, v79, s[16:17]
	v_add_f32_e32 v79, v201, v189
	v_cndmask_b32_e64 v196, v186, v79, s[18:19]
	s_waitcnt lgkmcnt(0)
	v_add_f32_e32 v79, v202, v190
	v_max3_f32 v78, v78, v131, v194
	v_cndmask_b32_e64 v197, v186, v79, s[20:21]
	v_add_f32_e32 v79, v203, v191
	v_max3_f32 v78, v78, v195, v196
	v_cndmask_b32_e64 v198, v186, v79, s[22:23]
	v_max3_f32 v199, v78, v197, v198
	v_add_u32_e32 v78, 0x498, v133
	ds_read2_b32 v[78:79], v78 offset1:1
	v_add_u32_e32 v80, 0x4a0, v133
	v_add_u32_e32 v188, 0x4a8, v133
	v_add_u32_e32 v190, 0x4b0, v133
	ds_read2_b32 v[80:81], v80 offset1:1
	ds_read2_b32 v[188:189], v188 offset1:1
	ds_read2_b32 v[190:191], v190 offset1:1
	s_waitcnt lgkmcnt(3)
	v_add_f32_e32 v78, v122, v78
	v_cndmask_b32_e32 v122, v186, v78, vcc
	v_add_f32_e32 v78, v123, v79
	s_waitcnt lgkmcnt(2)
	v_add_f32_e32 v79, v124, v80
	v_cndmask_b32_e64 v124, v186, v79, s[12:13]
	v_add_f32_e32 v79, v125, v81
	v_cndmask_b32_e64 v125, v186, v79, s[14:15]
	s_waitcnt lgkmcnt(1)
	v_add_f32_e32 v79, v118, v188
	v_cndmask_b32_e64 v123, v186, v78, s[10:11]
	v_cndmask_b32_e64 v188, v186, v79, s[16:17]
	v_add_f32_e32 v79, v119, v189
	v_max3_f32 v78, v199, v122, v123
	v_cndmask_b32_e64 v189, v186, v79, s[18:19]
	s_waitcnt lgkmcnt(0)
	v_add_f32_e32 v79, v120, v190
	v_max3_f32 v78, v78, v124, v125
	v_cndmask_b32_e64 v190, v186, v79, s[20:21]
	v_add_f32_e32 v79, v121, v191
	v_max3_f32 v78, v78, v188, v189
	v_cndmask_b32_e64 v191, v186, v79, s[22:23]
	v_max3_f32 v199, v78, v190, v191
	v_add_u32_e32 v78, 0x514, v133
	ds_read2_b32 v[78:79], v78 offset1:1
	v_add_u32_e32 v80, 0x51c, v133
	v_add_u32_e32 v118, 0x524, v133
	v_add_u32_e32 v120, 0x52c, v133
	ds_read2_b32 v[80:81], v80 offset1:1
	ds_read2_b32 v[118:119], v118 offset1:1
	ds_read2_b32 v[120:121], v120 offset1:1
	s_waitcnt lgkmcnt(3)
	v_add_f32_e32 v78, v110, v78
	v_cndmask_b32_e32 v200, v186, v78, vcc
	v_add_f32_e32 v78, v111, v79
	v_cndmask_b32_e64 v201, v186, v78, s[10:11]
	s_waitcnt lgkmcnt(2)
	v_add_f32_e32 v79, v112, v80
	v_max3_f32 v78, v199, v200, v201
	v_cndmask_b32_e64 v199, v186, v79, s[12:13]
	v_add_f32_e32 v79, v113, v81
	v_cndmask_b32_e64 v202, v186, v79, s[14:15]
	s_waitcnt lgkmcnt(1)
	v_add_f32_e32 v79, v114, v118
	v_cndmask_b32_e64 v114, v186, v79, s[16:17]
	v_add_f32_e32 v79, v115, v119
	v_cndmask_b32_e64 v115, v186, v79, s[18:19]
	s_waitcnt lgkmcnt(0)
	v_add_f32_e32 v79, v116, v120
	v_max3_f32 v78, v78, v199, v202
	v_cndmask_b32_e64 v116, v186, v79, s[20:21]
	v_add_f32_e32 v79, v117, v121
	v_max3_f32 v78, v78, v114, v115
	v_cndmask_b32_e64 v117, v186, v79, s[22:23]
	v_max3_f32 v118, v78, v116, v117
	v_add_u32_e32 v78, 0x590, v133
	ds_read2_b32 v[78:79], v78 offset1:1
	v_add_u32_e32 v80, 0x598, v133
	v_add_u32_e32 v110, 0x5a0, v133
	v_add_u32_e32 v112, 0x5a8, v133
	ds_read2_b32 v[80:81], v80 offset1:1
	ds_read2_b32 v[110:111], v110 offset1:1
	ds_read2_b32 v[112:113], v112 offset1:1
	s_waitcnt lgkmcnt(3)
	v_add_f32_e32 v78, v102, v78
	v_cndmask_b32_e32 v119, v186, v78, vcc
	v_add_f32_e32 v78, v103, v79
	v_cndmask_b32_e64 v120, v186, v78, s[10:11]
	s_waitcnt lgkmcnt(2)
	v_add_f32_e32 v79, v104, v80
	v_max3_f32 v78, v118, v119, v120
	v_cndmask_b32_e64 v118, v186, v79, s[12:13]
	v_add_f32_e32 v79, v105, v81
	v_cndmask_b32_e64 v121, v186, v79, s[14:15]
	s_waitcnt lgkmcnt(1)
	v_add_f32_e32 v79, v106, v110
	v_cndmask_b32_e64 v106, v186, v79, s[16:17]
	v_add_f32_e32 v79, v107, v111
	v_cndmask_b32_e64 v107, v186, v79, s[18:19]
	s_waitcnt lgkmcnt(0)
	v_add_f32_e32 v79, v108, v112
	v_max3_f32 v78, v78, v118, v121
	v_cndmask_b32_e64 v108, v186, v79, s[20:21]
	v_add_f32_e32 v79, v109, v113
	v_max3_f32 v78, v78, v106, v107
	v_cndmask_b32_e64 v109, v186, v79, s[22:23]
	v_max3_f32 v110, v78, v108, v109
	v_add_u32_e32 v78, 0x60c, v133
	ds_read2_b32 v[78:79], v78 offset1:1
	v_add_u32_e32 v80, 0x614, v133
	v_add_u32_e32 v102, 0x61c, v133
	v_add_u32_e32 v104, 0x624, v133
	ds_read2_b32 v[80:81], v80 offset1:1
	ds_read2_b32 v[102:103], v102 offset1:1
	ds_read2_b32 v[104:105], v104 offset1:1
	s_waitcnt lgkmcnt(3)
	v_add_f32_e32 v78, v94, v78
	v_cndmask_b32_e32 v94, v186, v78, vcc
	v_add_f32_e32 v78, v95, v79
	s_waitcnt lgkmcnt(2)
	v_add_f32_e32 v79, v96, v80
	v_cndmask_b32_e64 v96, v186, v79, s[12:13]
	v_add_f32_e32 v79, v97, v81
	v_cndmask_b32_e64 v97, v186, v79, s[14:15]
	s_waitcnt lgkmcnt(1)
	v_add_f32_e32 v79, v90, v102
	v_cndmask_b32_e64 v95, v186, v78, s[10:11]
	v_cndmask_b32_e64 v102, v186, v79, s[16:17]
	v_add_f32_e32 v79, v91, v103
	v_max3_f32 v78, v110, v94, v95
	v_cndmask_b32_e64 v103, v186, v79, s[18:19]
	s_waitcnt lgkmcnt(0)
	v_add_f32_e32 v79, v92, v104
	v_max3_f32 v78, v78, v96, v97
	v_cndmask_b32_e64 v104, v186, v79, s[20:21]
	v_add_f32_e32 v79, v93, v105
	v_max3_f32 v78, v78, v102, v103
	v_cndmask_b32_e64 v105, v186, v79, s[22:23]
	v_max3_f32 v110, v78, v104, v105
	v_add_u32_e32 v78, 0x688, v133
	ds_read2_b32 v[78:79], v78 offset1:1
	v_add_u32_e32 v80, 0x690, v133
	v_add_u32_e32 v90, 0x698, v133
	v_add_u32_e32 v92, 0x6a0, v133
	ds_read2_b32 v[80:81], v80 offset1:1
	ds_read2_b32 v[90:91], v90 offset1:1
	ds_read2_b32 v[92:93], v92 offset1:1
	s_waitcnt lgkmcnt(3)
	v_add_f32_e32 v78, v82, v78
	v_cndmask_b32_e32 v111, v186, v78, vcc
	v_add_f32_e32 v78, v83, v79
	v_cndmask_b32_e64 v112, v186, v78, s[10:11]
	s_waitcnt lgkmcnt(2)
	v_add_f32_e32 v79, v84, v80
	v_max3_f32 v78, v110, v111, v112
	v_cndmask_b32_e64 v110, v186, v79, s[12:13]
	v_add_f32_e32 v79, v85, v81
	v_cndmask_b32_e64 v113, v186, v79, s[14:15]
	s_waitcnt lgkmcnt(1)
	v_add_f32_e32 v79, v98, v90
	v_cndmask_b32_e64 v203, v186, v79, s[16:17]
	v_add_f32_e32 v79, v99, v91
	v_cndmask_b32_e64 v204, v186, v79, s[18:19]
	s_waitcnt lgkmcnt(0)
	v_add_f32_e32 v79, v100, v92
	v_max3_f32 v78, v78, v110, v113
	v_cndmask_b32_e64 v205, v186, v79, s[20:21]
	v_add_f32_e32 v79, v101, v93
	v_max3_f32 v78, v78, v203, v204
	v_cndmask_b32_e64 v206, v186, v79, s[22:23]
	v_max3_f32 v90, v78, v205, v206
	v_add_u32_e32 v78, 0x704, v133
	ds_read2_b32 v[78:79], v78 offset1:1
	v_add_u32_e32 v80, 0x70c, v133
	v_add_u32_e32 v82, 0x714, v133
	v_add_u32_e32 v84, 0x71c, v133
	ds_read2_b32 v[80:81], v80 offset1:1
	ds_read2_b32 v[82:83], v82 offset1:1
	ds_read2_b32 v[84:85], v84 offset1:1
	s_waitcnt lgkmcnt(3)
	v_add_f32_e32 v78, v86, v78
	v_cndmask_b32_e32 v133, v186, v78, vcc
	v_add_f32_e32 v78, v87, v79
	s_waitcnt lgkmcnt(2)
	v_add_f32_e32 v79, v88, v80
	v_cndmask_b32_e64 v207, v186, v78, s[10:11]
	v_cndmask_b32_e64 v208, v186, v79, s[12:13]
	v_add_f32_e32 v79, v89, v81
	s_waitcnt lgkmcnt(1)
	v_add_f32_e32 v74, v74, v82
	v_max3_f32 v78, v90, v133, v207
	v_cndmask_b32_e64 v209, v186, v79, s[14:15]
	v_cndmask_b32_e64 v210, v186, v74, s[16:17]
	v_add_f32_e32 v74, v75, v83
	s_waitcnt lgkmcnt(0)
	v_add_f32_e32 v75, v76, v84
	v_max3_f32 v78, v78, v208, v209
	v_cndmask_b32_e64 v211, v186, v74, s[18:19]
	v_cndmask_b32_e64 v212, v186, v75, s[20:21]
	v_add_f32_e32 v75, v77, v85
	v_max3_f32 v74, v78, v210, v211
	v_cndmask_b32_e64 v213, v186, v75, s[22:23]
	v_max3_f32 v74, v74, v212, v213
	v_mov_b32_e32 v75, v74
	v_add_u32_e32 v90, s46, v181
	s_add_u32 s0, s38, s0
	s_addc_u32 s1, s39, 0
	s_mov_b32 s14, s36
	v_permlane16_swap_b32_e32 v74, v75
	v_max_f32_e32 v75, v75, v75
	v_max_f32_e32 v74, v74, v75
	v_mov_b32_e32 v75, v74
	s_mov_b32 s15, s35
	s_nop 1
	v_permlane32_swap_b32_e32 v74, v75
	v_max_f32_e32 v75, v75, v75
	v_max_f32_e32 v214, v74, v75
	v_sub_f32_e32 v74, v137, v214
	v_exp_f32_e32 v78, v74
	v_sub_f32_e32 v74, v139, v214
	v_exp_f32_e32 v79, v74
	v_sub_f32_e32 v74, v155, v214
	v_exp_f32_e32 v80, v74
	v_sub_f32_e32 v74, v157, v214
	v_exp_f32_e32 v81, v74
	v_sub_f32_e32 v75, v141, v214
	v_add_f32_e32 v74, 0, v78
	v_exp_f32_e32 v86, v75
	v_sub_f32_e32 v75, v187, v214
	v_add_f32_e32 v74, v79, v74
	v_exp_f32_e32 v87, v75
	v_sub_f32_e32 v75, v192, v214
	v_add_f32_e32 v74, v80, v74
	v_exp_f32_e32 v88, v75
	v_sub_f32_e32 v75, v129, v214
	v_add_f32_e32 v74, v81, v74
	v_exp_f32_e32 v89, v75
	v_sub_f32_e32 v75, v135, v214
	v_add_f32_e32 v74, v86, v74
	v_exp_f32_e32 v98, v75
	v_sub_f32_e32 v75, v193, v214
	v_add_f32_e32 v74, v87, v74
	v_exp_f32_e32 v99, v75
	v_sub_f32_e32 v75, v131, v214
	v_add_f32_e32 v74, v88, v74
	v_exp_f32_e32 v129, v75
	v_sub_f32_e32 v75, v194, v214
	v_add_f32_e32 v74, v89, v74
	v_exp_f32_e32 v131, v75
	v_sub_f32_e32 v75, v195, v214
	v_add_f32_e32 v74, v98, v74
	v_exp_f32_e32 v135, v75
	v_sub_f32_e32 v75, v196, v214
	v_add_f32_e32 v74, v99, v74
	v_exp_f32_e32 v137, v75
	v_sub_f32_e32 v75, v197, v214
	v_add_f32_e32 v74, v129, v74
	v_exp_f32_e32 v139, v75
	v_sub_f32_e32 v75, v198, v214
	v_add_f32_e32 v74, v131, v74
	v_exp_f32_e32 v141, v75
	v_sub_f32_e32 v75, v122, v214
	v_add_f32_e32 v74, v135, v74
	v_exp_f32_e32 v122, v75
	v_sub_f32_e32 v75, v123, v214
	v_add_f32_e32 v74, v137, v74
	v_exp_f32_e32 v123, v75
	v_sub_f32_e32 v75, v124, v214
	v_add_f32_e32 v74, v139, v74
	v_exp_f32_e32 v124, v75
	v_sub_f32_e32 v75, v125, v214
	v_add_f32_e32 v74, v141, v74
	v_exp_f32_e32 v125, v75
	v_sub_f32_e32 v75, v188, v214
	v_add_f32_e32 v74, v122, v74
	v_exp_f32_e32 v155, v75
	v_sub_f32_e32 v75, v189, v214
	v_add_f32_e32 v74, v123, v74
	v_exp_f32_e32 v157, v75
	v_sub_f32_e32 v75, v190, v214
	v_add_f32_e32 v74, v124, v74
	v_exp_f32_e32 v187, v75
	v_sub_f32_e32 v75, v191, v214
	v_add_f32_e32 v74, v125, v74
	v_exp_f32_e32 v188, v75
	v_sub_f32_e32 v75, v200, v214
	v_add_f32_e32 v74, v155, v74
	v_exp_f32_e32 v189, v75
	v_sub_f32_e32 v75, v201, v214
	v_add_f32_e32 v74, v157, v74
	v_exp_f32_e32 v190, v75
	v_sub_f32_e32 v75, v199, v214
	v_add_f32_e32 v74, v187, v74
	v_exp_f32_e32 v191, v75
	v_sub_f32_e32 v75, v202, v214
	v_add_f32_e32 v74, v188, v74
	v_exp_f32_e32 v192, v75
	v_sub_f32_e32 v75, v114, v214
	v_add_f32_e32 v74, v189, v74
	v_exp_f32_e32 v114, v75
	v_sub_f32_e32 v75, v115, v214
	v_add_f32_e32 v74, v190, v74
	v_exp_f32_e32 v115, v75
	v_sub_f32_e32 v75, v116, v214
	v_add_f32_e32 v74, v191, v74
	v_exp_f32_e32 v116, v75
	v_sub_f32_e32 v75, v117, v214
	v_add_f32_e32 v74, v192, v74
	v_exp_f32_e32 v117, v75
	v_sub_f32_e32 v75, v119, v214
	v_add_f32_e32 v74, v114, v74
	v_exp_f32_e32 v119, v75
	v_sub_f32_e32 v75, v120, v214
	v_add_f32_e32 v74, v115, v74
	v_exp_f32_e32 v120, v75
	v_sub_f32_e32 v75, v118, v214
	v_add_f32_e32 v74, v116, v74
	v_exp_f32_e32 v118, v75
	v_sub_f32_e32 v75, v121, v214
	v_add_f32_e32 v74, v117, v74
	v_exp_f32_e32 v121, v75
	v_sub_f32_e32 v75, v106, v214
	v_add_f32_e32 v74, v119, v74
	v_exp_f32_e32 v106, v75
	v_sub_f32_e32 v75, v107, v214
	v_add_f32_e32 v74, v120, v74
	v_exp_f32_e32 v107, v75
	v_sub_f32_e32 v75, v108, v214
	v_add_f32_e32 v74, v118, v74
	v_exp_f32_e32 v108, v75
	v_sub_f32_e32 v75, v109, v214
	v_add_f32_e32 v74, v121, v74
	v_exp_f32_e32 v109, v75
	v_sub_f32_e32 v75, v94, v214
	v_add_f32_e32 v74, v106, v74
	v_exp_f32_e32 v193, v75
	v_sub_f32_e32 v75, v95, v214
	v_add_f32_e32 v74, v107, v74
	v_exp_f32_e32 v194, v75
	v_sub_f32_e32 v75, v96, v214
	v_add_f32_e32 v74, v108, v74
	v_exp_f32_e32 v195, v75
	v_sub_f32_e32 v75, v97, v214
	v_add_f32_e32 v74, v109, v74
	v_exp_f32_e32 v196, v75
	v_add_f32_e32 v74, v193, v74
	v_add_f32_e32 v74, v194, v74
	v_add_f32_e32 v74, v195, v74
	v_add_f32_e32 v82, v196, v74
	v_sub_f32_e32 v74, v102, v214
	v_exp_f32_e32 v102, v74
	v_sub_f32_e32 v74, v103, v214
	v_exp_f32_e32 v103, v74
	v_sub_f32_e32 v91, v104, v214
	v_exp_f32_e32 v104, v91
	v_sub_f32_e32 v91, v105, v214
	v_exp_f32_e32 v105, v91
	v_add_f32_e32 v82, v102, v82
	v_add_f32_e32 v94, v103, v82
	v_add_f32_e32 v94, v104, v94
	v_sub_f32_e32 v100, v111, v214
	v_add_u32_e32 v111, s47, v181
	ds_read_b128 v[74:77], v90 offset:61440
	ds_read_b128 v[82:85], v90 offset:62464
	v_cvt_pk_bf16_f32 v78, v78, v79
	v_cvt_pk_bf16_f32 v79, v80, v81
	v_cvt_pk_bf16_f32 v80, v86, v87
	v_cvt_pk_bf16_f32 v81, v88, v89
	ds_read_b128 v[86:89], v90 offset:63488
	v_add_f32_e32 v197, v105, v94
	ds_read_b128 v[94:97], v111 offset:61440
	ds_read_b128 v[90:93], v90 offset:64512
	s_waitcnt lgkmcnt(4)
	v_mfma_f32_16x16x32_bf16 v[74:77], v[74:77], v[78:81], 0
	v_exp_f32_e32 v198, v100
	v_sub_f32_e32 v112, v112, v214
	v_exp_f32_e32 v112, v112
	s_waitcnt lgkmcnt(3)
	v_mfma_f32_16x16x32_bf16 v[82:85], v[82:85], v[78:81], 0
	v_sub_f32_e32 v110, v110, v214
	v_exp_f32_e32 v110, v110
	v_sub_f32_e32 v113, v113, v214
	s_waitcnt lgkmcnt(2)
	v_mfma_f32_16x16x32_bf16 v[86:89], v[86:89], v[78:81], 0
	v_exp_f32_e32 v113, v113
	s_waitcnt lgkmcnt(0)
	v_mfma_f32_16x16x32_bf16 v[78:81], v[90:93], v[78:81], 0
	v_cvt_pk_bf16_f32 v90, v98, v99
	ds_read_b128 v[98:101], v111 offset:62464
	v_cvt_pk_bf16_f32 v91, v129, v131
	v_cvt_pk_bf16_f32 v92, v135, v137
	v_cvt_pk_bf16_f32 v93, v139, v141
	v_add_u32_e32 v129, s45, v181
	s_nop 0
	v_mfma_f32_16x16x32_bf16 v[74:77], v[94:97], v[90:93], v[74:77]
	ds_read_b128 v[94:97], v111 offset:63488
	s_waitcnt lgkmcnt(1)
	v_mfma_f32_16x16x32_bf16 v[82:85], v[98:101], v[90:93], v[82:85]
	ds_read_b128 v[98:101], v111 offset:64512
	s_waitcnt lgkmcnt(1)
	v_mfma_f32_16x16x32_bf16 v[86:89], v[94:97], v[90:93], v[86:89]
	ds_read_b128 v[94:97], v129 offset:61440
	v_add_f32_e32 v111, v198, v197
	v_add_f32_e32 v111, v112, v111
	s_waitcnt lgkmcnt(1)
	v_mfma_f32_16x16x32_bf16 v[78:81], v[98:101], v[90:93], v[78:81]
	ds_read_b128 v[98:101], v129 offset:62464
	v_cvt_pk_bf16_f32 v90, v122, v123
	v_cvt_pk_bf16_f32 v91, v124, v125
	v_cvt_pk_bf16_f32 v92, v155, v157
	v_cvt_pk_bf16_f32 v93, v187, v188
	v_add_u32_e32 v124, s44, v181
	v_sub_f32_e32 v122, v203, v214
	s_waitcnt lgkmcnt(1)
	v_mfma_f32_16x16x32_bf16 v[74:77], v[94:97], v[90:93], v[74:77]
	ds_read_b128 v[94:97], v129 offset:63488
	v_exp_f32_e32 v122, v122
	v_sub_f32_e32 v123, v204, v214
	s_waitcnt lgkmcnt(1)
	v_mfma_f32_16x16x32_bf16 v[82:85], v[98:101], v[90:93], v[82:85]
	ds_read_b128 v[98:101], v129 offset:64512
	v_exp_f32_e32 v123, v123
	v_sub_f32_e32 v125, v205, v214
	s_waitcnt lgkmcnt(1)
	v_mfma_f32_16x16x32_bf16 v[86:89], v[94:97], v[90:93], v[86:89]
	ds_read_b128 v[94:97], v124 offset:61440
	v_add_f32_e32 v111, v110, v111
	v_add_f32_e32 v111, v113, v111
	s_waitcnt lgkmcnt(1)
	v_mfma_f32_16x16x32_bf16 v[78:81], v[98:101], v[90:93], v[78:81]
	ds_read_b128 v[98:101], v124 offset:62464
	v_cvt_pk_bf16_f32 v90, v189, v190
	v_cvt_pk_bf16_f32 v91, v191, v192
	v_cvt_pk_bf16_f32 v92, v114, v115
	v_cvt_pk_bf16_f32 v93, v116, v117
	v_add_u32_e32 v117, s43, v181
	v_exp_f32_e32 v114, v125
	s_waitcnt lgkmcnt(1)
	v_mfma_f32_16x16x32_bf16 v[74:77], v[94:97], v[90:93], v[74:77]
	ds_read_b128 v[94:97], v124 offset:63488
	v_sub_f32_e32 v115, v206, v214
	v_exp_f32_e32 v115, v115
	s_waitcnt lgkmcnt(1)
	v_mfma_f32_16x16x32_bf16 v[82:85], v[98:101], v[90:93], v[82:85]
	ds_read_b128 v[98:101], v124 offset:64512
	v_sub_f32_e32 v116, v133, v214
	v_add_f32_e32 v111, v122, v111
	s_waitcnt lgkmcnt(1)
	v_mfma_f32_16x16x32_bf16 v[86:89], v[94:97], v[90:93], v[86:89]
	ds_read_b128 v[94:97], v117 offset:61440
	v_exp_f32_e32 v116, v116
	v_add_f32_e32 v111, v123, v111
	s_waitcnt lgkmcnt(1)
	v_mfma_f32_16x16x32_bf16 v[78:81], v[98:101], v[90:93], v[78:81]
	ds_read_b128 v[98:101], v117 offset:62464
	v_cvt_pk_bf16_f32 v90, v119, v120
	v_cvt_pk_bf16_f32 v91, v118, v121
	v_cvt_pk_bf16_f32 v92, v106, v107
	v_cvt_pk_bf16_f32 v93, v108, v109
	v_add_u32_e32 v109, s42, v181
	v_add_f32_e32 v111, v114, v111
	s_waitcnt lgkmcnt(1)
	v_mfma_f32_16x16x32_bf16 v[74:77], v[94:97], v[90:93], v[74:77]
	ds_read_b128 v[94:97], v117 offset:63488
	v_sub_f32_e32 v124, v207, v214
	v_add_f32_e32 v111, v115, v111
	s_waitcnt lgkmcnt(1)
	v_mfma_f32_16x16x32_bf16 v[82:85], v[98:101], v[90:93], v[82:85]
	ds_read_b128 v[98:101], v117 offset:64512
	v_exp_f32_e32 v106, v124
	v_sub_f32_e32 v107, v208, v214
	s_waitcnt lgkmcnt(1)
	v_mfma_f32_16x16x32_bf16 v[86:89], v[94:97], v[90:93], v[86:89]
	ds_read_b128 v[94:97], v109 offset:61440
	v_exp_f32_e32 v107, v107
	v_add_f32_e32 v108, v116, v111
	s_waitcnt lgkmcnt(1)
	v_mfma_f32_16x16x32_bf16 v[78:81], v[98:101], v[90:93], v[78:81]
	ds_read_b128 v[98:101], v109 offset:62464
	v_cvt_pk_bf16_f32 v90, v193, v194
	v_cvt_pk_bf16_f32 v91, v195, v196
	v_cvt_pk_bf16_f32 v92, v102, v103
	v_cvt_pk_bf16_f32 v93, v104, v105
	v_add_u32_e32 v105, s41, v181
	v_sub_f32_e32 v111, v209, v214
	s_waitcnt lgkmcnt(1)
	v_mfma_f32_16x16x32_bf16 v[74:77], v[94:97], v[90:93], v[74:77]
	ds_read_b128 v[94:97], v109 offset:63488
	v_exp_f32_e32 v111, v111
	v_add_f32_e32 v108, v106, v108
	s_waitcnt lgkmcnt(1)
	v_mfma_f32_16x16x32_bf16 v[82:85], v[98:101], v[90:93], v[82:85]
	ds_read_b128 v[98:101], v109 offset:64512
	v_sub_f32_e32 v102, v210, v214
	v_add_f32_e32 v108, v107, v108
	s_waitcnt lgkmcnt(1)
	v_mfma_f32_16x16x32_bf16 v[86:89], v[94:97], v[90:93], v[86:89]
	ds_read_b128 v[94:97], v105 offset:61440
	v_exp_f32_e32 v102, v102
	v_sub_f32_e32 v104, v211, v214
	s_waitcnt lgkmcnt(1)
	v_mfma_f32_16x16x32_bf16 v[78:81], v[98:101], v[90:93], v[78:81]
	ds_read_b128 v[98:101], v105 offset:62464
	v_add_f32_e32 v103, v111, v108
	v_exp_f32_e32 v104, v104
	v_sub_f32_e32 v108, v212, v214
	v_cvt_pk_bf16_f32 v90, v198, v112
	v_cvt_pk_bf16_f32 v91, v110, v113
	v_cvt_pk_bf16_f32 v92, v122, v123
	v_cvt_pk_bf16_f32 v93, v114, v115
	v_exp_f32_e32 v108, v108
	v_sub_f32_e32 v109, v213, v214
	s_waitcnt lgkmcnt(1)
	v_mfma_f32_16x16x32_bf16 v[74:77], v[94:97], v[90:93], v[74:77]
	ds_read_b128 v[94:97], v105 offset:63488
	v_exp_f32_e32 v109, v109
	v_add_f32_e32 v103, v102, v103
	s_waitcnt lgkmcnt(1)
	v_mfma_f32_16x16x32_bf16 v[82:85], v[98:101], v[90:93], v[82:85]
	ds_read_b128 v[98:101], v105 offset:64512
	v_add_f32_e32 v103, v104, v103
	v_add_f32_e32 v103, v108, v103
	v_add_f32_e32 v103, v109, v103
	ds_bpermute_b32 v105, v179, v103
	s_waitcnt lgkmcnt(1)
	v_mfma_f32_16x16x32_bf16 v[78:81], v[98:101], v[90:93], v[78:81]
	v_cvt_pk_bf16_f32 v100, v102, v104
	v_lshlrev_b32_e32 v102, 2, v144
	v_lshl_or_b32 v120, s37, 8, v102
	s_waitcnt lgkmcnt(0)
	v_add_f32_e32 v112, v103, v105
	global_load_dwordx4 v[102:105], v120, s[72:73]
	global_load_dwordx4 v[240:243], v120, s[72:73] offset:64
	global_load_dwordx4 v[244:247], v120, s[72:73] offset:128
	global_load_dwordx4 v[248:251], v120, s[72:73] offset:192
	v_add_u32_e32 v110, s40, v181
	v_mfma_f32_16x16x32_bf16 v[86:89], v[94:97], v[90:93], v[86:89]
	ds_read_b128 v[94:97], v110 offset:61440
	ds_read_b128 v[90:93], v110 offset:62464
	v_cvt_pk_bf16_f32 v98, v116, v106
	v_cvt_pk_bf16_f32 v99, v107, v111
	v_cvt_pk_bf16_f32 v101, v108, v109
	ds_bpermute_b32 v106, v180, v112
	v_and_b32_e32 v113, 0xffff0000, v163
	s_waitcnt lgkmcnt(2)
	v_mfma_f32_16x16x32_bf16 v[94:97], v[94:97], v[98:101], v[74:77]
	v_mov_b32_e32 v157, v127
	s_nop 1
	ds_read_b128 v[74:77], v110 offset:63488
	s_waitcnt lgkmcnt(2)
	v_mfma_f32_16x16x32_bf16 v[82:85], v[90:93], v[98:101], v[82:85]
	ds_read_b128 v[90:93], v110 offset:64512
	s_waitcnt lgkmcnt(1)
	v_mfma_f32_16x16x32_bf16 v[86:89], v[74:77], v[98:101], v[86:89]
	v_add_f32_e32 v74, v112, v106
	v_rcp_f32_e32 v106, v74
	v_lshlrev_b32_e32 v112, 16, v163
	s_waitcnt lgkmcnt(0)
	v_mfma_f32_16x16x32_bf16 v[76:79], v[90:93], v[98:101], v[78:81]
	v_lshlrev_b32_e32 v100, 16, v162
	v_pk_mul_f32 v[96:97], v[96:97], v[106:107] op_sel_hi:[1,0]
	v_pk_mul_f32 v[94:95], v[94:95], v[106:107] op_sel_hi:[1,0]
	v_and_b32_e32 v101, 0xffff0000, v162
	v_mul_f32_e32 v108, 0xbfb8aa3b, v101
	s_nop 2
	v_pk_mul_f32 v[76:77], v[76:77], v[106:107] op_sel_hi:[1,0]
	v_pk_mul_f32 v[74:75], v[78:79], v[106:107] op_sel_hi:[1,0]
	v_mul_f32_e32 v107, 0xbfb8aa3b, v100
	v_exp_f32_e32 v107, v107
	v_exp_f32_e32 v111, v108
	v_pk_mul_f32 v[108:109], v[94:95], v[94:95]
	v_pk_mul_f32 v[98:99], v[96:97], v[96:97]
	v_add_f32_e32 v107, 1.0, v107
	v_rcp_f32_e32 v110, v107
	v_add_f32_e32 v107, 1.0, v111
	v_add_f32_e32 v108, v108, v109
	v_pk_mul_f32 v[82:83], v[82:83], v[106:107] op_sel_hi:[1,0]
	v_add_f32_e32 v98, v98, v108
	v_pk_mul_f32 v[116:117], v[82:83], v[82:83]
	v_add_f32_e32 v98, v99, v98
	v_pk_mul_f32 v[84:85], v[84:85], v[106:107] op_sel_hi:[1,0]
	v_add_f32_e32 v98, v116, v98
	v_pk_mul_f32 v[114:115], v[84:85], v[84:85]
	v_add_f32_e32 v98, v117, v98
	v_pk_mul_f32 v[86:87], v[86:87], v[106:107] op_sel_hi:[1,0]
	v_add_f32_e32 v98, v114, v98
	v_rcp_f32_e32 v111, v107
	v_pk_mul_f32 v[88:89], v[88:89], v[106:107] op_sel_hi:[1,0]
	v_pk_mul_f32 v[106:107], v[86:87], v[86:87]
	v_add_f32_e32 v98, v115, v98
	v_add_f32_e32 v98, v106, v98
	v_pk_mul_f32 v[118:119], v[88:89], v[88:89]
	v_add_f32_e32 v98, v107, v98
	v_add_f32_e32 v98, v118, v98
	v_pk_mul_f32 v[80:81], v[76:77], v[76:77]
	v_add_f32_e32 v98, v119, v98
	v_add_f32_e32 v80, v80, v98
	v_pk_mul_f32 v[78:79], v[74:75], v[74:75]
	v_add_f32_e32 v80, v81, v80
	v_add_f32_e32 v78, v78, v80
	v_add_f32_e32 v78, v79, v78
	v_mov_b32_e32 v79, v78
	v_mul_f32_e32 v80, 0xbfb8aa3b, v112
	v_exp_f32_e32 v80, v80
	v_mul_f32_e32 v81, 0xbfb8aa3b, v113
	v_exp_f32_e32 v81, v81
	v_permlane16_swap_b32_e32 v78, v79
	v_add_f32_e32 v98, v78, v79
	v_mov_b32_e32 v99, v98
	v_add_f32_e32 v78, 1.0, v80
	v_add_f32_e32 v79, 1.0, v81
	v_lshl_add_u64 v[90:91], s[0:1], 0, v[156:157]
	v_lshlrev_b32_e32 v92, 1, v144
	v_permlane32_swap_b32_e32 v98, v99
	v_add_f32_e32 v80, v98, v99
	v_fmamk_f32 v80, v80, 0x3c800000, v185
	v_mul_f32_e32 v81, 0x4b800000, v80
	v_cmp_gt_f32_e32 vcc, s34, v80
	v_mov_b32_e32 v93, v127
	v_lshl_add_u64 v[90:91], v[90:91], 0, v[92:93]
	v_cndmask_b32_e32 v80, v80, v81, vcc
	v_rsq_f32_e32 v98, v80
	v_rcp_f32_e32 v78, v78
	v_rcp_f32_e32 v79, v79
	v_pk_mul_f32 v[80:81], v[110:111], v[100:101]
	v_mul_f32_e32 v92, 0x45800000, v98
	v_cndmask_b32_e32 v92, v98, v92, vcc
	v_pk_mul_f32 v[94:95], v[94:95], v[92:93] op_sel_hi:[1,0]
	v_pk_mul_f32 v[78:79], v[78:79], v[112:113]
	s_waitcnt vmcnt(0)
	v_pk_mul_f32 v[94:95], v[102:103], v[94:95]
	v_lshlrev_b32_e32 v98, 16, v161
	v_pk_mul_f32 v[80:81], v[80:81], v[94:95]
	v_pk_mul_f32 v[94:95], v[96:97], v[92:93] op_sel_hi:[1,0]
	v_cvt_pk_bf16_f32 v80, v80, v81
	v_pk_mul_f32 v[94:95], v[104:105], v[94:95]
	v_and_b32_e32 v99, 0xffff0000, v161
	v_pk_mul_f32 v[78:79], v[78:79], v[94:95]
	v_lshlrev_b32_e32 v94, 16, v160
	v_cvt_pk_bf16_f32 v81, v78, v79
	global_store_dwordx2 v[90:91], v[80:81], off
	v_and_b32_e32 v95, 0xffff0000, v160
	v_mul_f32_e32 v93, 0xbfb8aa3b, v94
	v_exp_f32_e32 v93, v93
	v_mul_f32_e32 v96, 0xbfb8aa3b, v95
	v_exp_f32_e32 v97, v96
	s_and_b64 vcc, exec, s[28:29]
	v_add_f32_e32 v93, 1.0, v93
	v_rcp_f32_e32 v96, v93
	v_add_f32_e32 v93, 1.0, v97
	v_mul_f32_e32 v97, 0xbfb8aa3b, v98
	v_exp_f32_e32 v100, v97
	v_mul_f32_e32 v97, 0xbfb8aa3b, v99
	v_exp_f32_e32 v101, v97
	v_rcp_f32_e32 v97, v93
	v_add_f32_e32 v93, 1.0, v100
	v_rcp_f32_e32 v100, v93
	v_add_f32_e32 v93, 1.0, v101
	v_rcp_f32_e32 v101, v93
	v_pk_mul_f32 v[82:83], v[82:83], v[92:93] op_sel_hi:[1,0]
	v_pk_mul_f32 v[94:95], v[96:97], v[94:95]
	v_pk_mul_f32 v[76:77], v[76:77], v[92:93] op_sel_hi:[1,0]
	v_pk_mul_f32 v[96:97], v[100:101], v[98:99]
	v_pk_mul_f32 v[74:75], v[74:75], v[92:93] op_sel_hi:[1,0]
	v_mov_b64_e32 v[160:161], v[166:167]
	v_mov_b64_e32 v[162:163], v[164:165]
	v_pk_mul_f32 v[78:79], v[240:241], v[82:83]
	v_pk_mul_f32 v[82:83], v[84:85], v[92:93] op_sel_hi:[1,0]
	v_pk_mul_f32 v[78:79], v[94:95], v[78:79]
	v_pk_mul_f32 v[80:81], v[242:243], v[82:83]
	v_cvt_pk_bf16_f32 v78, v78, v79
	v_pk_mul_f32 v[80:81], v[96:97], v[80:81]
	v_lshlrev_b32_e32 v82, 16, v158
	v_cvt_pk_bf16_f32 v79, v80, v81
	global_store_dwordx2 v[90:91], v[78:79], off offset:32
	v_and_b32_e32 v83, 0xffff0000, v158
	v_mul_f32_e32 v84, 0xbfb8aa3b, v82
	v_mul_f32_e32 v85, 0xbfb8aa3b, v83
	v_exp_f32_e32 v84, v84
	v_exp_f32_e32 v85, v85
	v_add_f32_e32 v84, 1.0, v84
	v_add_f32_e32 v85, 1.0, v85
	v_rcp_f32_e32 v84, v84
	v_rcp_f32_e32 v85, v85
	s_nop 0
	v_pk_mul_f32 v[82:83], v[84:85], v[82:83]
	v_pk_mul_f32 v[84:85], v[86:87], v[92:93] op_sel_hi:[1,0]
	v_pk_mul_f32 v[78:79], v[244:245], v[84:85]
	v_lshlrev_b32_e32 v84, 16, v159
	v_and_b32_e32 v85, 0xffff0000, v159
	v_mul_f32_e32 v86, 0xbfb8aa3b, v84
	v_mul_f32_e32 v87, 0xbfb8aa3b, v85
	v_exp_f32_e32 v86, v86
	v_exp_f32_e32 v87, v87
	v_pk_mul_f32 v[78:79], v[82:83], v[78:79]
	v_mov_b64_e32 v[158:159], v[168:169]
	v_add_f32_e32 v82, 1.0, v86
	v_add_f32_e32 v83, 1.0, v87
	v_rcp_f32_e32 v82, v82
	v_rcp_f32_e32 v83, v83
	v_pk_mul_f32 v[86:87], v[88:89], v[92:93] op_sel_hi:[1,0]
	v_cvt_pk_bf16_f32 v78, v78, v79
	v_pk_mul_f32 v[80:81], v[246:247], v[86:87]
	v_pk_mul_f32 v[82:83], v[82:83], v[84:85]
	s_nop 0
	v_pk_mul_f32 v[80:81], v[82:83], v[80:81]
	v_lshlrev_b32_e32 v82, 16, v146
	v_cvt_pk_bf16_f32 v79, v80, v81
	global_store_dwordx2 v[90:91], v[78:79], off offset:64
	v_and_b32_e32 v83, 0xffff0000, v146
	v_mul_f32_e32 v84, 0xbfb8aa3b, v82
	v_mul_f32_e32 v85, 0xbfb8aa3b, v83
	v_exp_f32_e32 v84, v84
	v_exp_f32_e32 v85, v85
	v_add_f32_e32 v84, 1.0, v84
	v_add_f32_e32 v85, 1.0, v85
	v_rcp_f32_e32 v84, v84
	v_rcp_f32_e32 v85, v85
	v_pk_mul_f32 v[76:77], v[248:249], v[76:77]
	v_pk_mul_f32 v[78:79], v[84:85], v[82:83]
	v_lshlrev_b32_e32 v82, 16, v147
	v_and_b32_e32 v83, 0xffff0000, v147
	v_mul_f32_e32 v84, 0xbfb8aa3b, v82
	v_mul_f32_e32 v85, 0xbfb8aa3b, v83
	v_exp_f32_e32 v84, v84
	v_exp_f32_e32 v85, v85
	v_pk_mul_f32 v[76:77], v[78:79], v[76:77]
	v_pk_mul_f32 v[74:75], v[250:251], v[74:75]
	v_add_f32_e32 v78, 1.0, v84
	v_add_f32_e32 v79, 1.0, v85
	v_rcp_f32_e32 v78, v78
	v_rcp_f32_e32 v79, v79
	v_cvt_pk_bf16_f32 v76, v76, v77
	v_mov_b64_e32 v[146:147], v[170:171]
	v_pk_mul_f32 v[78:79], v[78:79], v[82:83]
	s_nop 0
	v_pk_mul_f32 v[74:75], v[78:79], v[74:75]
	v_mov_b64_e32 v[80:81], v[68:69]
	v_cvt_pk_bf16_f32 v77, v74, v75
	global_store_dwordx2 v[90:91], v[76:77], off offset:96
	v_mov_b64_e32 v[76:77], v[72:73]
	v_mov_b64_e32 v[74:75], v[70:71]
	v_mov_b64_e32 v[78:79], v[66:67]
	s_cbranch_vccnz .LBB0_461
